# EpiUp: per-row rstd (IEEE sqrt+div) computed once per row per wave (2 of 8 row-blocks per lane, gathered by ds_bpermute) instead of 8x redundantly
# speedup vs baseline: 1.0197x; 1.0082x over previous
;     __device__ __forceinline__ void operator()(const pg8::f32x4 (&acc)[2][2][4][2], const Unit& u, int wr, int wc, int fr, int fq) const {
;         const int rbase = u.pm * 256 + wr * 64 + fr, col = u.pn * 128 + wc * 32 + 8 * fq; bf16* HID = (bf16*)(c.ws + WS_HID); const float* SS = (const float*)(c.ws + WS_SS1);
; #pragma unroll
;         for (int ai = 0; ai < 2; ++ai)
; #pragma unroll
;             for (int m = 0; m < 4; ++m) { const int row = rbase + ai * 128 + m * 16; const f32x4* sp = (const f32x4*)(SS + (size_t)row * 16);
;                 const f32x4 a = sp[0], b = sp[1], cc = sp[2], dd = sp[3];
;                 const float tot = ((a[0] + a[1]) + (a[2] + a[3])) + ((b[0] + b[1]) + (b[2] + b[3])) + ((cc[0] + cc[1]) + (cc[2] + cc[3])) + ((dd[0] + dd[1]) + (dd[2] + dd[3]));
;                 const float rstd = 1.f / sqrtf(tot * (1.f / D) + 1e-6f);
.LBB0_1260:
	v_lshl_add_u32 v144, s4, 8, v146
	v_mbcnt_lo_u32_b32 v214, -1, 0
	v_mbcnt_hi_u32_b32 v214, -1, v214
	v_and_b32_e32 v215, 48, v214
	v_and_b32_e32 v216, 15, v214
	v_lshl_add_u32 v220, v144, 6, v215
	v_lshlrev_b32_e32 v216, 2, v216
	v_add_u32_e32 v221, 0x2000, v220
	global_load_dwordx4 v[178:181], v220, s[18:19]
	global_load_dwordx4 v[182:185], v220, s[18:19] offset:1024
	global_load_dwordx4 v[186:189], v220, s[18:19] offset:2048
	global_load_dwordx4 v[190:193], v220, s[18:19] offset:3072
	global_load_dwordx4 v[194:197], v221, s[18:19]
	global_load_dwordx4 v[198:201], v221, s[18:19] offset:1024
	global_load_dwordx4 v[202:205], v221, s[18:19] offset:2048
	global_load_dwordx4 v[206:209], v221, s[18:19] offset:3072
	v_add_u32_e32 v217, 64, v216
	v_add_u32_e32 v218, 0x80, v216
	v_add_u32_e32 v219, 0xc0, v216
	s_waitcnt vmcnt(7)
	v_add_f32_e32 v178, v178, v179
	v_add_f32_e32 v180, v180, v181
	v_add_f32_e32 v178, v178, v180
	ds_bpermute_b32 v179, v216, v178
	ds_bpermute_b32 v180, v217, v178
	ds_bpermute_b32 v181, v218, v178
	ds_bpermute_b32 v236, v219, v178
	s_waitcnt vmcnt(6)
	v_add_f32_e32 v182, v182, v183
	v_add_f32_e32 v184, v184, v185
	v_add_f32_e32 v182, v182, v184
	ds_bpermute_b32 v183, v216, v182
	ds_bpermute_b32 v184, v217, v182
	ds_bpermute_b32 v185, v218, v182
	ds_bpermute_b32 v237, v219, v182
	s_waitcnt lgkmcnt(4)
	v_add_f32_e32 v228, v179, v180
	v_add_f32_e32 v228, v228, v181
	v_add_f32_e32 v228, v228, v236
	s_waitcnt vmcnt(5)
	v_add_f32_e32 v186, v186, v187
	v_add_f32_e32 v188, v188, v189
	v_add_f32_e32 v186, v186, v188
	ds_bpermute_b32 v187, v216, v186
	ds_bpermute_b32 v188, v217, v186
	ds_bpermute_b32 v189, v218, v186
	ds_bpermute_b32 v238, v219, v186
	s_waitcnt lgkmcnt(4)
	v_add_f32_e32 v229, v183, v184
	v_add_f32_e32 v229, v229, v185
	v_add_f32_e32 v229, v229, v237
	s_waitcnt vmcnt(4)
	v_add_f32_e32 v190, v190, v191
	v_add_f32_e32 v192, v192, v193
	v_add_f32_e32 v190, v190, v192
	ds_bpermute_b32 v191, v216, v190
	ds_bpermute_b32 v192, v217, v190
	ds_bpermute_b32 v193, v218, v190
	ds_bpermute_b32 v239, v219, v190
	s_waitcnt lgkmcnt(4)
	v_add_f32_e32 v230, v187, v188
	v_add_f32_e32 v230, v230, v189
	v_add_f32_e32 v230, v230, v238
	s_waitcnt vmcnt(3)
	v_add_f32_e32 v194, v194, v195
	v_add_f32_e32 v196, v196, v197
	v_add_f32_e32 v194, v194, v196
	ds_bpermute_b32 v195, v216, v194
	ds_bpermute_b32 v196, v217, v194
	ds_bpermute_b32 v197, v218, v194
	ds_bpermute_b32 v240, v219, v194
	s_waitcnt lgkmcnt(4)
	v_add_f32_e32 v231, v191, v192
	v_add_f32_e32 v231, v231, v193
	v_add_f32_e32 v231, v231, v239
	s_waitcnt vmcnt(2)
	v_add_f32_e32 v198, v198, v199
	v_add_f32_e32 v200, v200, v201
	v_add_f32_e32 v198, v198, v200
	ds_bpermute_b32 v199, v216, v198
	ds_bpermute_b32 v200, v217, v198
	ds_bpermute_b32 v201, v218, v198
	ds_bpermute_b32 v241, v219, v198
	s_waitcnt lgkmcnt(4)
	v_add_f32_e32 v232, v195, v196
	v_add_f32_e32 v232, v232, v197
	v_add_f32_e32 v232, v232, v240
	s_waitcnt vmcnt(1)
	v_add_f32_e32 v202, v202, v203
	v_add_f32_e32 v204, v204, v205
	v_add_f32_e32 v202, v202, v204
	ds_bpermute_b32 v203, v216, v202
	ds_bpermute_b32 v204, v217, v202
	ds_bpermute_b32 v205, v218, v202
	ds_bpermute_b32 v242, v219, v202
	s_waitcnt lgkmcnt(4)
	v_add_f32_e32 v233, v199, v200
	v_add_f32_e32 v233, v233, v201
	v_add_f32_e32 v233, v233, v241
	s_waitcnt vmcnt(0)
	v_add_f32_e32 v206, v206, v207
	v_add_f32_e32 v208, v208, v209
	v_add_f32_e32 v206, v206, v208
	ds_bpermute_b32 v207, v216, v206
	ds_bpermute_b32 v208, v217, v206
	ds_bpermute_b32 v209, v218, v206
	ds_bpermute_b32 v243, v219, v206
	s_waitcnt lgkmcnt(4)
	v_add_f32_e32 v234, v203, v204
	v_add_f32_e32 v234, v234, v205
	v_add_f32_e32 v234, v234, v242
	s_waitcnt lgkmcnt(0)
	v_add_f32_e32 v235, v207, v208
	v_add_f32_e32 v235, v235, v209
	v_add_f32_e32 v235, v235, v243
	v_cmp_eq_u32_e64 s[98:99], 16, v215
	v_cmp_eq_u32_e64 s[100:101], 32, v215
	v_cmp_eq_u32_e32 vcc, 48, v215
	s_nop 1
	v_cndmask_b32_e64 v244, v228, v230, s[98:99]
	v_cndmask_b32_e64 v245, v229, v231, s[98:99]
	v_cndmask_b32_e64 v244, v244, v232, s[100:101]
	v_cndmask_b32_e64 v245, v245, v233, s[100:101]
	v_cndmask_b32_e32 v244, v244, v234, vcc
	v_cndmask_b32_e32 v245, v245, v235, vcc
	v_fmamk_f32 v194, v244, 0x3a800000, v152
	v_mul_f32_e32 v195, 0x4f800000, v194
	v_cmp_gt_f32_e32 vcc, s62, v194
	s_nop 1
	v_cndmask_b32_e32 v195, v194, v195, vcc
	v_sqrt_f32_e32 v196, v195
	s_nop 0
	v_add_u32_e32 v197, -1, v196
	v_add_u32_e32 v198, 1, v196
	v_fma_f32 v199, -v197, v196, v195
	v_fma_f32 v200, -v198, v196, v195
	v_cmp_ge_f32_e64 s[98:99], 0, v199
	s_nop 1
	v_cndmask_b32_e64 v196, v196, v197, s[98:99]
	v_cmp_lt_f32_e64 s[98:99], 0, v200
	s_nop 1
	v_cndmask_b32_e64 v196, v196, v198, s[98:99]
	v_mul_f32_e32 v197, 0x37800000, v196
	v_cndmask_b32_e32 v196, v196, v197, vcc
	v_cmp_class_f32_e32 vcc, v195, v153
	s_nop 1
	v_cndmask_b32_e32 v197, v196, v195, vcc
	v_div_scale_f32 v198, s[98:99], v197, v197, 1.0
	v_rcp_f32_e32 v199, v198
	v_div_scale_f32 v200, vcc, 1.0, v197, 1.0
	v_fma_f32 v194, -v198, v199, 1.0
	v_fmac_f32_e32 v199, v194, v199
	v_mul_f32_e32 v194, v200, v199
	v_fma_f32 v195, -v198, v194, v200
	v_fmac_f32_e32 v194, v195, v199
	v_fma_f32 v198, -v198, v194, v200
	v_div_fmas_f32 v198, v198, v199, v194
	v_div_fixup_f32 v246, v198, v197, 1.0
	v_fmamk_f32 v201, v245, 0x3a800000, v152
	v_mul_f32_e32 v202, 0x4f800000, v201
	v_cmp_gt_f32_e32 vcc, s62, v201
	s_nop 1
	v_cndmask_b32_e32 v202, v201, v202, vcc
	v_sqrt_f32_e32 v203, v202
	s_nop 0
	v_add_u32_e32 v204, -1, v203
	v_add_u32_e32 v205, 1, v203
	v_fma_f32 v206, -v204, v203, v202
	v_fma_f32 v207, -v205, v203, v202
	v_cmp_ge_f32_e64 s[98:99], 0, v206
	s_nop 1
	v_cndmask_b32_e64 v203, v203, v204, s[98:99]
	v_cmp_lt_f32_e64 s[98:99], 0, v207
	s_nop 1
	v_cndmask_b32_e64 v203, v203, v205, s[98:99]
	v_mul_f32_e32 v204, 0x37800000, v203
	v_cndmask_b32_e32 v203, v203, v204, vcc
	v_cmp_class_f32_e32 vcc, v202, v153
	s_nop 1
	v_cndmask_b32_e32 v204, v203, v202, vcc
	v_div_scale_f32 v205, s[98:99], v204, v204, 1.0
	v_rcp_f32_e32 v206, v205
	v_div_scale_f32 v207, vcc, 1.0, v204, 1.0
	v_fma_f32 v201, -v205, v206, 1.0
	v_fmac_f32_e32 v206, v201, v206
	v_mul_f32_e32 v201, v207, v206
	v_fma_f32 v202, -v205, v201, v207
	v_fmac_f32_e32 v201, v202, v206
	v_fma_f32 v205, -v205, v201, v207
	v_div_fmas_f32 v205, v205, v206, v201
	v_div_fixup_f32 v247, v205, v204, 1.0
	ds_bpermute_b32 v178, v216, v246
	ds_bpermute_b32 v180, v216, v247
	ds_bpermute_b32 v182, v217, v246
	ds_bpermute_b32 v184, v217, v247
	ds_bpermute_b32 v186, v218, v246
	ds_bpermute_b32 v188, v218, v247
	ds_bpermute_b32 v190, v219, v246
	ds_bpermute_b32 v192, v219, v247
	s_waitcnt lgkmcnt(0)
; __device__ __forceinline__ float silu_f(float x) { return x * sigm_f(x); }
;     __device__ __forceinline__ void operator()(const pg8::f32x4 (&acc)[2][2][4][2], const Unit& u, int wr, int wc, int fr, int fq) const {
;     ...
;             for (int m = 0; m < 4; ++m) { const int row = rbase + ai * 128 + m * 16; const f32x4* sp = (const f32x4*)(SS + (size_t)row * 16);
;                 const f32x4 a = sp[0], b = sp[1], cc = sp[2], dd = sp[3];
;                 const float tot = ((a[0] + a[1]) + (a[2] + a[3])) + ((b[0] + b[1]) + (b[2] + b[3])) + ((cc[0] + cc[1]) + (cc[2] + cc[3])) + ((dd[0] + dd[1]) + (dd[2] + dd[3]));
;                 const float rstd = 1.f / sqrtf(tot * (1.f / D) + 1e-6f);
;                 f32x4 h0, h1;
; #pragma unroll
;                 for (int j = 0; j < 4; ++j) { h0[j] = silu_f(acc[ai][0][m][0][j] * rstd) * (acc[ai][1][m][0][j] * rstd); h1[j] = silu_f(acc[ai][0][m][1][j] * rstd) * (acc[ai][1][m][1][j] * rstd); }
;                 *(u32x4*)(HID + (size_t)row * DFF + col) = pack8(h0, h1); }
	v_ashrrev_i32_e32 v145, 31, v144
	v_lshlrev_b64 v[154:155], 6, v[144:145]
	v_lshl_add_u64 v[166:167], s[18:19], 0, v[154:155]
	v_mov_b32_e32 v174, v116
	v_mov_b32_e32 v175, v112
	v_mov_b32_e32 v112, v117
	v_mov_b32_e32 v177, v114
	v_mov_b32_e32 v176, v118
	v_mov_b32_e32 v172, v124
	v_mov_b32_e32 v124, v126
	v_lshl_or_b32 v170, s5, 7, v148
	v_mov_b32_e32 v173, v120
	v_mov_b32_e32 v120, v125
	v_mov_b32_e32 v125, v122
	v_mov_b32_e32 v122, v127
	v_ashrrev_i32_e32 v171, 31, v170
	s_nop 0
	s_nop 0
	s_nop 1
	v_mov_b32_e32 v114, v119
	s_nop 1
	s_nop 1
	s_nop 1
	v_lshl_add_u64 v[116:117], v[170:171], 1, s[30:31]
	v_pk_mul_f32 v[126:127], v[172:173], v[178:179] op_sel_hi:[1,0]
	v_pk_mul_f32 v[154:155], v[174:175], v[178:179] op_sel_hi:[1,0]
	v_pk_mul_f32 v[120:121], v[120:121], v[178:179] op_sel_hi:[1,0]
	v_pk_mul_f32 v[112:113], v[112:113], v[178:179] op_sel_hi:[1,0]
	v_pk_mul_f32 v[124:125], v[124:125], v[178:179] op_sel_hi:[1,0]
	v_pk_mul_f32 v[156:157], v[176:177], v[178:179] op_sel_hi:[1,0]
	v_pk_mul_f32 v[122:123], v[122:123], v[178:179] op_sel_hi:[1,0]
	v_pk_mul_f32 v[114:115], v[114:115], v[178:179] op_sel_hi:[1,0]
	v_mul_f32_e32 v118, 0xbfb8aa3b, v127
	v_mul_f32_e32 v119, 0xbfb8aa3b, v155
	v_mul_f32_e32 v145, 0xbfb8aa3b, v121
	v_mul_f32_e32 v158, 0xbfb8aa3b, v113
	v_mul_f32_e32 v159, 0xbfb8aa3b, v125
	v_mul_f32_e32 v161, 0xbfb8aa3b, v123
	v_mul_f32_e32 v162, 0xbfb8aa3b, v115
	v_exp_f32_e32 v118, v118
	v_exp_f32_e32 v119, v119
	v_exp_f32_e32 v145, v145
	v_exp_f32_e32 v158, v158
	v_exp_f32_e32 v159, v159
	v_mul_f32_e32 v160, 0xbfb8aa3b, v157
	v_exp_f32_e32 v161, v161
	v_exp_f32_e32 v162, v162
	v_exp_f32_e32 v160, v160
	v_add_f32_e32 v118, 1.0, v118
	v_add_f32_e32 v119, 1.0, v119
	v_add_f32_e32 v145, 1.0, v145
	v_add_f32_e32 v158, 1.0, v158
	v_add_f32_e32 v159, 1.0, v159
	v_add_f32_e32 v161, 1.0, v161
	v_add_f32_e32 v162, 1.0, v162
	v_rcp_f32_e32 v118, v118
	v_rcp_f32_e32 v119, v119
	v_rcp_f32_e32 v145, v145
	v_rcp_f32_e32 v158, v158
	v_rcp_f32_e32 v159, v159
	v_add_f32_e32 v160, 1.0, v160
	v_rcp_f32_e32 v161, v161
	v_rcp_f32_e32 v162, v162
	v_rcp_f32_e32 v160, v160
	v_mul_f32_e32 v118, v127, v118
	v_mul_f32_e32 v119, v155, v119
	v_mul_f32_e32 v121, v121, v145
	v_mul_f32_e32 v113, v113, v158
	v_mul_f32_e32 v125, v125, v159
	v_mul_f32_e32 v123, v123, v161
	v_mul_f32_e32 v115, v115, v162
	v_mul_f32_e32 v118, v126, v118
	v_mul_f32_e32 v119, v154, v119
	v_mul_f32_e32 v120, v120, v121
	v_mul_f32_e32 v121, v112, v113
	v_mul_f32_e32 v113, v124, v125
	v_mul_f32_e32 v127, v157, v160
	v_mul_f32_e32 v122, v122, v123
	v_mul_f32_e32 v115, v114, v115
	v_cvt_pk_bf16_f32 v112, v118, v120
	v_cvt_pk_bf16_f32 v113, v113, v122
	v_cvt_pk_bf16_f32 v114, v119, v121
	v_mad_i64_i32 v[118:119], s[4:5], v144, s63, v[116:117]
	v_mul_f32_e32 v124, v156, v127
	v_cvt_pk_bf16_f32 v115, v124, v115
	global_store_dwordx4 v[118:119], v[112:115], off
	v_mov_b32_e32 v127, v100
	v_mov_b32_e32 v100, v97
	v_or_b32_e32 v112, 16, v144
	v_ashrrev_i32_e32 v113, 31, v112
	v_lshlrev_b64 v[114:115], 6, v[112:113]
	v_lshl_add_u64 v[114:115], s[18:19], 0, v[114:115]
	v_mov_b32_e32 v114, v108
	v_mov_b32_e32 v115, v104
	v_mov_b32_e32 v104, v109
	v_mov_b32_e32 v97, v106
	v_mov_b32_e32 v126, v96
	v_mov_b32_e32 v96, v110
	s_nop 0
	s_nop 0
	v_mov_b32_e32 v109, v102
	s_nop 0
	v_mov_b32_e32 v108, v98
	v_mov_b32_e32 v106, v111
	s_nop 1
	s_nop 1
	v_mov_b32_e32 v102, v99
	s_nop 0
	v_pk_mul_f32 v[96:97], v[96:97], v[180:181] op_sel_hi:[1,0]
	v_pk_mul_f32 v[104:105], v[104:105], v[180:181] op_sel_hi:[1,0]
	v_pk_mul_f32 v[106:107], v[106:107], v[180:181] op_sel_hi:[1,0]
	v_mul_f32_e32 v119, 0xbfb8aa3b, v97
	v_pk_mul_f32 v[110:111], v[114:115], v[180:181] op_sel_hi:[1,0]
	v_pk_mul_f32 v[114:115], v[126:127], v[180:181] op_sel_hi:[1,0]
	v_pk_mul_f32 v[100:101], v[100:101], v[180:181] op_sel_hi:[1,0]
	v_pk_mul_f32 v[108:109], v[108:109], v[180:181] op_sel_hi:[1,0]
	v_pk_mul_f32 v[98:99], v[102:103], v[180:181] op_sel_hi:[1,0]
	v_mul_f32_e32 v113, 0xbfb8aa3b, v105
	v_mul_f32_e32 v121, 0xbfb8aa3b, v107
	v_exp_f32_e32 v119, v119
	v_mul_f32_e32 v118, 0xbfb8aa3b, v101
	v_mul_f32_e32 v120, 0xbfb8aa3b, v109
	v_mul_f32_e32 v122, 0xbfb8aa3b, v99
	v_exp_f32_e32 v113, v113
	v_exp_f32_e32 v121, v121
	v_mul_f32_e32 v102, 0xbfb8aa3b, v111
	v_mul_f32_e32 v103, 0xbfb8aa3b, v115
	v_exp_f32_e32 v118, v118
	v_exp_f32_e32 v120, v120
	v_exp_f32_e32 v122, v122
	v_exp_f32_e32 v102, v102
	v_exp_f32_e32 v103, v103
	v_add_f32_e32 v119, 1.0, v119
	v_add_f32_e32 v113, 1.0, v113
	v_add_f32_e32 v121, 1.0, v121
	v_rcp_f32_e32 v119, v119
	v_add_f32_e32 v118, 1.0, v118
	v_add_f32_e32 v120, 1.0, v120
	v_add_f32_e32 v122, 1.0, v122
	v_rcp_f32_e32 v113, v113
	v_rcp_f32_e32 v121, v121
	v_add_f32_e32 v102, 1.0, v102
	v_add_f32_e32 v103, 1.0, v103
	v_rcp_f32_e32 v118, v118
	v_rcp_f32_e32 v120, v120
	v_rcp_f32_e32 v122, v122
	v_rcp_f32_e32 v102, v102
	v_rcp_f32_e32 v103, v103
	v_mul_f32_e32 v97, v97, v119
	v_mul_f32_e32 v105, v105, v113
	v_mul_f32_e32 v97, v96, v97
	v_mul_f32_e32 v96, v107, v121
	v_mul_f32_e32 v101, v101, v118
	v_mul_f32_e32 v109, v109, v120
	v_mul_f32_e32 v104, v104, v105
	v_mul_f32_e32 v105, v106, v96
	v_mul_f32_e32 v96, v99, v122
	v_mul_f32_e32 v102, v111, v102
	v_mul_f32_e32 v103, v115, v103
	v_mul_f32_e32 v100, v100, v101
	v_mul_f32_e32 v101, v108, v109
	v_mul_f32_e32 v99, v98, v96
	v_mul_f32_e32 v102, v110, v102
	v_mul_f32_e32 v103, v114, v103
	v_cvt_pk_bf16_f32 v96, v102, v104
	v_cvt_pk_bf16_f32 v97, v97, v105
	v_cvt_pk_bf16_f32 v98, v103, v100
	v_cvt_pk_bf16_f32 v99, v101, v99
	v_mad_i64_i32 v[100:101], s[4:5], v112, s63, v[116:117]
	global_store_dwordx4 v[100:101], v[96:99], off
	v_mov_b32_e32 v114, v92
	v_mov_b32_e32 v115, v88
; __device__ __forceinline__ float silu_f(float x) { return x * sigm_f(x); }
;     __device__ __forceinline__ void operator()(const pg8::f32x4 (&acc)[2][2][4][2], const Unit& u, int wr, int wc, int fr, int fq) const {
;     ...
;             for (int m = 0; m < 4; ++m) { const int row = rbase + ai * 128 + m * 16; const f32x4* sp = (const f32x4*)(SS + (size_t)row * 16);
;                 const f32x4 a = sp[0], b = sp[1], cc = sp[2], dd = sp[3];
;                 const float tot = ((a[0] + a[1]) + (a[2] + a[3])) + ((b[0] + b[1]) + (b[2] + b[3])) + ((cc[0] + cc[1]) + (cc[2] + cc[3])) + ((dd[0] + dd[1]) + (dd[2] + dd[3]));
;                 const float rstd = 1.f / sqrtf(tot * (1.f / D) + 1e-6f);
;                 f32x4 h0, h1;
; #pragma unroll
;                 for (int j = 0; j < 4; ++j) { h0[j] = silu_f(acc[ai][0][m][0][j] * rstd) * (acc[ai][1][m][0][j] * rstd); h1[j] = silu_f(acc[ai][0][m][1][j] * rstd) * (acc[ai][1][m][1][j] * rstd); }
;                 *(u32x4*)(HID + (size_t)row * DFF + col) = pack8(h0, h1); }
	v_or_b32_e32 v96, 32, v144
	v_ashrrev_i32_e32 v97, 31, v96
	v_lshlrev_b64 v[98:99], 6, v[96:97]
	v_lshl_add_u64 v[110:111], s[18:19], 0, v[98:99]
	v_mov_b32_e32 v88, v93
	v_mov_b32_e32 v119, v84
	v_mov_b32_e32 v84, v81
	v_mov_b32_e32 v81, v90
	v_mov_b32_e32 v118, v80
	v_mov_b32_e32 v80, v94
	s_nop 0
	s_nop 0
	v_mov_b32_e32 v93, v86
	s_nop 0
	v_mov_b32_e32 v92, v82
	v_mov_b32_e32 v90, v95
	s_nop 1
	s_nop 1
	v_mov_b32_e32 v86, v83
	s_nop 0
	v_pk_mul_f32 v[80:81], v[80:81], v[182:183] op_sel_hi:[1,0]
	v_pk_mul_f32 v[84:85], v[84:85], v[182:183] op_sel_hi:[1,0]
	v_mul_f32_e32 v101, 0xbfb8aa3b, v81
	v_mul_f32_e32 v100, 0xbfb8aa3b, v85
	v_exp_f32_e32 v101, v101
	v_exp_f32_e32 v100, v100
	v_pk_mul_f32 v[90:91], v[90:91], v[182:183] op_sel_hi:[1,0]
	v_pk_mul_f32 v[94:95], v[114:115], v[182:183] op_sel_hi:[1,0]
	v_add_f32_e32 v101, 1.0, v101
	v_pk_mul_f32 v[98:99], v[118:119], v[182:183] op_sel_hi:[1,0]
	v_pk_mul_f32 v[88:89], v[88:89], v[182:183] op_sel_hi:[1,0]
	v_pk_mul_f32 v[92:93], v[92:93], v[182:183] op_sel_hi:[1,0]
	v_pk_mul_f32 v[82:83], v[86:87], v[182:183] op_sel_hi:[1,0]
	v_mul_f32_e32 v103, 0xbfb8aa3b, v91
	v_add_f32_e32 v100, 1.0, v100
	v_rcp_f32_e32 v101, v101
	v_mul_f32_e32 v86, 0xbfb8aa3b, v95
	v_mul_f32_e32 v87, 0xbfb8aa3b, v99
	v_mul_f32_e32 v97, 0xbfb8aa3b, v89
	v_mul_f32_e32 v104, 0xbfb8aa3b, v83
	v_exp_f32_e32 v103, v103
	v_rcp_f32_e32 v100, v100
	v_mul_f32_e32 v102, 0xbfb8aa3b, v93
	v_exp_f32_e32 v86, v86
	v_exp_f32_e32 v87, v87
	v_exp_f32_e32 v97, v97
	v_exp_f32_e32 v104, v104
	v_exp_f32_e32 v102, v102
	v_mul_f32_e32 v81, v81, v101
	v_mul_f32_e32 v85, v85, v100
	v_mul_f32_e32 v81, v80, v81
	v_add_f32_e32 v80, 1.0, v103
	v_add_f32_e32 v86, 1.0, v86
	v_add_f32_e32 v87, 1.0, v87
	v_add_f32_e32 v97, 1.0, v97
	v_mul_f32_e32 v84, v84, v85
	v_rcp_f32_e32 v80, v80
	v_add_f32_e32 v85, 1.0, v104
	v_add_f32_e32 v102, 1.0, v102
	v_rcp_f32_e32 v86, v86
	v_rcp_f32_e32 v87, v87
	v_rcp_f32_e32 v97, v97
	v_rcp_f32_e32 v85, v85
	v_rcp_f32_e32 v102, v102
	v_mul_f32_e32 v80, v91, v80
	v_mul_f32_e32 v86, v95, v86
	v_mul_f32_e32 v87, v99, v87
	v_mul_f32_e32 v89, v89, v97
	v_mul_f32_e32 v90, v90, v80
	v_mul_f32_e32 v80, v83, v85
	v_mul_f32_e32 v93, v93, v102
	v_mul_f32_e32 v86, v94, v86
	v_mul_f32_e32 v87, v98, v87
	v_mul_f32_e32 v88, v88, v89
	v_mul_f32_e32 v83, v82, v80
	v_cvt_pk_bf16_f32 v80, v86, v88
	v_cvt_pk_bf16_f32 v81, v81, v90
	v_cvt_pk_bf16_f32 v82, v87, v84
	v_mad_i64_i32 v[84:85], s[4:5], v96, s63, v[116:117]
	v_mul_f32_e32 v89, v92, v93
	v_cvt_pk_bf16_f32 v83, v89, v83
	global_store_dwordx4 v[84:85], v[80:83], off
	v_mov_b32_e32 v98, v72
	v_mov_b32_e32 v99, v76
	v_or_b32_e32 v80, 48, v144
	v_ashrrev_i32_e32 v81, 31, v80
	v_lshlrev_b64 v[82:83], 6, v[80:81]
	v_lshl_add_u64 v[94:95], s[18:19], 0, v[82:83]
	v_mov_b32_e32 v76, v73
	v_mov_b32_e32 v101, v68
	v_mov_b32_e32 v68, v65
	v_mov_b32_e32 v100, v64
	v_mov_b32_e32 v64, v74
	s_nop 0
	s_nop 0
	v_mov_b32_e32 v73, v70
	s_nop 0
	v_mov_b32_e32 v72, v66
	v_mov_b32_e32 v65, v78
	v_mov_b32_e32 v78, v75
	s_nop 0
	s_nop 1
	s_nop 1
	v_pk_mul_f32 v[74:75], v[98:99], v[184:185] op_sel_hi:[1,0]
	v_pk_mul_f32 v[68:69], v[68:69], v[184:185] op_sel_hi:[1,0]
	v_pk_mul_f32 v[64:65], v[64:65], v[184:185] op_sel_hi:[1,0]
	v_mul_f32_e32 v70, 0xbfb8aa3b, v75
	v_mul_f32_e32 v85, 0xbfb8aa3b, v69
	v_mul_f32_e32 v86, 0xbfb8aa3b, v65
	v_exp_f32_e32 v70, v70
	v_exp_f32_e32 v85, v85
	v_exp_f32_e32 v86, v86
	v_pk_mul_f32 v[82:83], v[100:101], v[184:185] op_sel_hi:[1,0]
	v_add_f32_e32 v70, 1.0, v70
	v_add_f32_e32 v85, 1.0, v85
	v_add_f32_e32 v86, 1.0, v86
	v_rcp_f32_e32 v70, v70
	v_rcp_f32_e32 v85, v85
	v_rcp_f32_e32 v86, v86
	v_pk_mul_f32 v[76:77], v[76:77], v[184:185] op_sel_hi:[1,0]
	v_mul_f32_e32 v70, v75, v70
	v_mul_f32_e32 v69, v69, v85
	v_mul_f32_e32 v65, v65, v86
	v_mul_f32_e32 v74, v74, v70
	v_mov_b32_e32 v70, v67
	v_pk_mul_f32 v[72:73], v[72:73], v[184:185] op_sel_hi:[1,0]
	v_pk_mul_f32 v[78:79], v[78:79], v[184:185] op_sel_hi:[1,0]
	v_mul_f32_e32 v68, v68, v69
	v_mul_f32_e32 v69, v64, v65
	v_pk_mul_f32 v[64:65], v[70:71], v[184:185] op_sel_hi:[1,0]
	v_mul_f32_e32 v81, 0xbfb8aa3b, v83
	v_mul_f32_e32 v84, 0xbfb8aa3b, v77
	v_mul_f32_e32 v87, 0xbfb8aa3b, v73
	v_mul_f32_e32 v88, 0xbfb8aa3b, v79
	v_mul_f32_e32 v66, 0xbfb8aa3b, v65
	v_exp_f32_e32 v81, v81
	v_exp_f32_e32 v84, v84
	v_exp_f32_e32 v87, v87
	v_exp_f32_e32 v88, v88
	v_exp_f32_e32 v66, v66
	v_add_f32_e32 v81, 1.0, v81
	v_add_f32_e32 v84, 1.0, v84
	v_add_f32_e32 v87, 1.0, v87
	v_add_f32_e32 v70, 1.0, v88
	v_add_f32_e32 v66, 1.0, v66
	v_rcp_f32_e32 v81, v81
	v_rcp_f32_e32 v84, v84
	v_rcp_f32_e32 v87, v87
	v_rcp_f32_e32 v70, v70
	v_rcp_f32_e32 v66, v66
	v_mul_f32_e32 v75, v83, v81
	v_mul_f32_e32 v77, v77, v84
	v_mul_f32_e32 v67, v73, v87
	v_mul_f32_e32 v70, v79, v70
	v_mul_f32_e32 v65, v65, v66
	v_mul_f32_e32 v75, v82, v75
	v_mul_f32_e32 v76, v76, v77
	v_mul_f32_e32 v67, v72, v67
	v_mul_f32_e32 v70, v78, v70
	v_mul_f32_e32 v71, v64, v65
	v_cvt_pk_bf16_f32 v64, v74, v76
	v_cvt_pk_bf16_f32 v65, v69, v70
	v_cvt_pk_bf16_f32 v66, v75, v68
	v_mad_i64_i32 v[68:69], s[4:5], v80, s63, v[116:117]
	v_cvt_pk_bf16_f32 v67, v67, v71
	global_store_dwordx4 v[68:69], v[64:67], off
	v_mov_b32_e32 v82, v52
	v_mov_b32_e32 v83, v60
	v_add_u32_e32 v64, 0x80, v144
	v_ashrrev_i32_e32 v65, 31, v64
	v_lshlrev_b64 v[66:67], 6, v[64:65]
	v_lshl_add_u64 v[78:79], s[18:19], 0, v[66:67]
	v_mov_b32_e32 v84, v48
	v_mov_b32_e32 v85, v56
	v_mov_b32_e32 v60, v53
	v_mov_b32_e32 v56, v49
	v_mov_b32_e32 v52, v50
	s_nop 0
	s_nop 1
	v_mov_b32_e32 v48, v54
	v_mov_b32_e32 v49, v62
	s_nop 1
	s_nop 1
	s_nop 1
	v_mov_b32_e32 v53, v58
	v_pk_mul_f32 v[68:69], v[84:85], v[186:187] op_sel_hi:[1,0]
; __device__ __forceinline__ float silu_f(float x) { return x * sigm_f(x); }
;     __device__ __forceinline__ void operator()(const pg8::f32x4 (&acc)[2][2][4][2], const Unit& u, int wr, int wc, int fr, int fq) const {
;     ...
;             for (int m = 0; m < 4; ++m) { const int row = rbase + ai * 128 + m * 16; const f32x4* sp = (const f32x4*)(SS + (size_t)row * 16);
;                 const f32x4 a = sp[0], b = sp[1], cc = sp[2], dd = sp[3];
;                 const float tot = ((a[0] + a[1]) + (a[2] + a[3])) + ((b[0] + b[1]) + (b[2] + b[3])) + ((cc[0] + cc[1]) + (cc[2] + cc[3])) + ((dd[0] + dd[1]) + (dd[2] + dd[3]));
;                 const float rstd = 1.f / sqrtf(tot * (1.f / D) + 1e-6f);
;                 f32x4 h0, h1;
; #pragma unroll
;                 for (int j = 0; j < 4; ++j) { h0[j] = silu_f(acc[ai][0][m][0][j] * rstd) * (acc[ai][1][m][0][j] * rstd); h1[j] = silu_f(acc[ai][0][m][1][j] * rstd) * (acc[ai][1][m][1][j] * rstd); }
;                 *(u32x4*)(HID + (size_t)row * DFF + col) = pack8(h0, h1); }
	v_pk_mul_f32 v[60:61], v[60:61], v[186:187] op_sel_hi:[1,0]
	v_pk_mul_f32 v[56:57], v[56:57], v[186:187] op_sel_hi:[1,0]
	v_pk_mul_f32 v[48:49], v[48:49], v[186:187] op_sel_hi:[1,0]
	v_mul_f32_e32 v58, 0xbfb8aa3b, v69
	v_mul_f32_e32 v62, 0xbfb8aa3b, v61
	v_mul_f32_e32 v65, 0xbfb8aa3b, v57
	v_mul_f32_e32 v70, 0xbfb8aa3b, v49
	v_exp_f32_e32 v58, v58
	v_exp_f32_e32 v62, v62
	v_exp_f32_e32 v65, v65
	v_exp_f32_e32 v70, v70
	v_add_f32_e32 v58, 1.0, v58
	v_add_f32_e32 v62, 1.0, v62
	v_add_f32_e32 v65, 1.0, v65
	v_add_f32_e32 v70, 1.0, v70
	v_rcp_f32_e32 v58, v58
	v_rcp_f32_e32 v62, v62
	v_rcp_f32_e32 v65, v65
	v_rcp_f32_e32 v70, v70
	v_mul_f32_e32 v58, v69, v58
	v_mul_f32_e32 v61, v61, v62
	v_mul_f32_e32 v57, v57, v65
	v_mul_f32_e32 v49, v49, v70
	v_mov_b32_e32 v62, v55
	v_mul_f32_e32 v65, v68, v58
	v_mul_f32_e32 v56, v56, v57
	v_mul_f32_e32 v57, v48, v49
	v_pk_mul_f32 v[48:49], v[62:63], v[186:187] op_sel_hi:[1,0]
	v_mov_b32_e32 v58, v51
	v_pk_mul_f32 v[66:67], v[82:83], v[186:187] op_sel_hi:[1,0]
	v_pk_mul_f32 v[52:53], v[52:53], v[186:187] op_sel_hi:[1,0]
	v_mul_f32_e32 v55, 0xbfb8aa3b, v49
	v_pk_mul_f32 v[50:51], v[58:59], v[186:187] op_sel_hi:[1,0]
	v_mul_f32_e32 v71, 0xbfb8aa3b, v53
	v_exp_f32_e32 v55, v55
	v_mul_f32_e32 v58, 0xbfb8aa3b, v51
	v_mul_f32_e32 v54, 0xbfb8aa3b, v67
	v_exp_f32_e32 v71, v71
	v_exp_f32_e32 v58, v58
	v_exp_f32_e32 v54, v54
	v_add_f32_e32 v55, 1.0, v55
	v_add_f32_e32 v71, 1.0, v71
	v_rcp_f32_e32 v55, v55
	v_add_f32_e32 v58, 1.0, v58
	v_add_f32_e32 v54, 1.0, v54
	v_mul_f32_e32 v60, v60, v61
	v_rcp_f32_e32 v61, v71
	v_rcp_f32_e32 v58, v58
	v_rcp_f32_e32 v54, v54
	v_mul_f32_e32 v49, v49, v55
	v_mul_f32_e32 v53, v53, v61
	v_mul_f32_e32 v49, v48, v49
	v_mul_f32_e32 v48, v51, v58
	v_mul_f32_e32 v54, v67, v54
	v_mul_f32_e32 v52, v52, v53
	v_mul_f32_e32 v51, v50, v48
	v_mul_f32_e32 v54, v66, v54
	v_cvt_pk_bf16_f32 v48, v54, v60
	v_cvt_pk_bf16_f32 v49, v57, v49
	v_cvt_pk_bf16_f32 v50, v65, v56
	v_cvt_pk_bf16_f32 v51, v52, v51
	v_mad_i64_i32 v[52:53], s[4:5], v64, s63, v[116:117]
	global_store_dwordx4 v[52:53], v[48:51], off
	v_mov_b32_e32 v66, v36
	v_mov_b32_e32 v67, v44
	v_add_u32_e32 v48, 0x90, v144
	v_ashrrev_i32_e32 v49, 31, v48
	v_lshlrev_b64 v[50:51], 6, v[48:49]
	v_lshl_add_u64 v[62:63], s[18:19], 0, v[50:51]
	v_mov_b32_e32 v68, v32
	v_mov_b32_e32 v69, v40
	v_mov_b32_e32 v44, v37
	v_mov_b32_e32 v40, v33
	v_mov_b32_e32 v36, v34
	s_nop 0
	s_nop 1
	v_mov_b32_e32 v32, v38
	v_mov_b32_e32 v33, v46
	s_nop 1
	s_nop 1
	s_nop 1
	v_mov_b32_e32 v37, v42
	v_pk_mul_f32 v[52:53], v[68:69], v[188:189] op_sel_hi:[1,0]
	v_pk_mul_f32 v[40:41], v[40:41], v[188:189] op_sel_hi:[1,0]
	v_mul_f32_e32 v42, 0xbfb8aa3b, v53
	v_mul_f32_e32 v49, 0xbfb8aa3b, v41
	v_exp_f32_e32 v42, v42
	v_exp_f32_e32 v49, v49
	v_pk_mul_f32 v[32:33], v[32:33], v[188:189] op_sel_hi:[1,0]
	v_pk_mul_f32 v[44:45], v[44:45], v[188:189] op_sel_hi:[1,0]
	v_mul_f32_e32 v54, 0xbfb8aa3b, v33
	v_mul_f32_e32 v46, 0xbfb8aa3b, v45
	v_exp_f32_e32 v54, v54
	v_add_f32_e32 v42, 1.0, v42
	v_exp_f32_e32 v46, v46
	v_add_f32_e32 v49, 1.0, v49
	v_rcp_f32_e32 v42, v42
	v_rcp_f32_e32 v49, v49
	v_pk_mul_f32 v[36:37], v[36:37], v[188:189] op_sel_hi:[1,0]
	v_add_f32_e32 v54, 1.0, v54
	v_mul_f32_e32 v55, 0xbfb8aa3b, v37
	v_add_f32_e32 v46, 1.0, v46
	v_rcp_f32_e32 v54, v54
	v_mul_f32_e32 v42, v53, v42
	v_rcp_f32_e32 v46, v46
	v_mul_f32_e32 v41, v41, v49
	v_mul_f32_e32 v49, v52, v42
	v_exp_f32_e32 v42, v55
	v_mul_f32_e32 v33, v33, v54
	v_mul_f32_e32 v45, v45, v46
	v_mul_f32_e32 v40, v40, v41
	v_mul_f32_e32 v41, v32, v33
	v_add_f32_e32 v32, 1.0, v42
	v_mov_b32_e32 v46, v39
	v_mul_f32_e32 v44, v44, v45
	v_rcp_f32_e32 v45, v32
	v_pk_mul_f32 v[32:33], v[46:47], v[188:189] op_sel_hi:[1,0]
	v_mov_b32_e32 v42, v35
	v_pk_mul_f32 v[50:51], v[66:67], v[188:189] op_sel_hi:[1,0]
	v_mul_f32_e32 v39, 0xbfb8aa3b, v33
	v_pk_mul_f32 v[34:35], v[42:43], v[188:189] op_sel_hi:[1,0]
	v_exp_f32_e32 v39, v39
	v_mul_f32_e32 v42, 0xbfb8aa3b, v35
	v_mul_f32_e32 v38, 0xbfb8aa3b, v51
	v_exp_f32_e32 v42, v42
	v_exp_f32_e32 v38, v38
	v_add_f32_e32 v39, 1.0, v39
	v_rcp_f32_e32 v39, v39
	v_add_f32_e32 v42, 1.0, v42
	v_add_f32_e32 v38, 1.0, v38
	v_rcp_f32_e32 v42, v42
	v_rcp_f32_e32 v38, v38
	v_mul_f32_e32 v33, v33, v39
	v_mul_f32_e32 v37, v37, v45
	v_mul_f32_e32 v33, v32, v33
	v_mul_f32_e32 v32, v35, v42
	v_mul_f32_e32 v38, v51, v38
	v_mul_f32_e32 v36, v36, v37
	v_mul_f32_e32 v35, v34, v32
	v_mul_f32_e32 v38, v50, v38
	v_cvt_pk_bf16_f32 v32, v38, v44
	v_cvt_pk_bf16_f32 v33, v41, v33
	v_cvt_pk_bf16_f32 v34, v49, v40
	v_cvt_pk_bf16_f32 v35, v36, v35
	v_mad_i64_i32 v[36:37], s[4:5], v48, s63, v[116:117]
	v_add_u32_e32 v48, 0xa0, v144
	v_ashrrev_i32_e32 v49, 31, v48
	global_store_dwordx4 v[36:37], v[32:35], off
	v_mov_b32_e32 v52, v16
	v_mov_b32_e32 v50, v20
	v_lshlrev_b64 v[32:33], 6, v[48:49]
	v_lshl_add_u64 v[44:45], s[18:19], 0, v[32:33]
	v_mov_b32_e32 v53, v24
	v_mov_b32_e32 v24, v17
	v_mov_b32_e32 v51, v28
	v_mov_b32_e32 v28, v21
; #define PG8_BAR __builtin_amdgcn_s_barrier()
; __device__ __forceinline__ float silu_f(float x) { return x * sigm_f(x); }
; template <class Epi, class Sched, bool ALIGN_EPI = false, bool SP2 = false>
; __device__ __forceinline__ void gemm_phase(PG8_LAS unsigned char* lds, const Gemm g, const Sched& S, const Epi& E, int wave_s) {
;     ...
;         if (!has_next) break;
; #pragma unroll
;         for (int a = 0; a < 2; ++a)
; #pragma unroll
;             for (int b = 0; b < 2; ++b)
; #pragma unroll
;                 for (int m = 0; m < 4; ++m)
; #pragma unroll
;                     for (int n = 0; n < 2; ++n) acc[a][b][m][n] = (f32x4){0.f, 0.f, 0.f, 0.f};
;         cur = nxt; cA = nA; cB = nB; ++ui;
;         if constexpr (ALIGN_EPI) { if (wr == 1) PG8_BAR; }
;     __device__ __forceinline__ void operator()(const pg8::f32x4 (&acc)[2][2][4][2], const Unit& u, int wr, int wc, int fr, int fq) const {
;     ...
;             for (int m = 0; m < 4; ++m) { const int row = rbase + ai * 128 + m * 16; const f32x4* sp = (const f32x4*)(SS + (size_t)row * 16);
;                 const f32x4 a = sp[0], b = sp[1], cc = sp[2], dd = sp[3];
;                 const float tot = ((a[0] + a[1]) + (a[2] + a[3])) + ((b[0] + b[1]) + (b[2] + b[3])) + ((cc[0] + cc[1]) + (cc[2] + cc[3])) + ((dd[0] + dd[1]) + (dd[2] + dd[3]));
;                 const float rstd = 1.f / sqrtf(tot * (1.f / D) + 1e-6f);
;                 f32x4 h0, h1;
; #pragma unroll
;                 for (int j = 0; j < 4; ++j) { h0[j] = silu_f(acc[ai][0][m][0][j] * rstd) * (acc[ai][1][m][0][j] * rstd); h1[j] = silu_f(acc[ai][0][m][1][j] * rstd) * (acc[ai][1][m][1][j] * rstd); }
;                 *(u32x4*)(HID + (size_t)row * DFF + col) = pack8(h0, h1); }
	s_nop 0
	s_nop 0
	s_nop 1
	v_mov_b32_e32 v16, v22
	s_nop 1
	s_nop 1
	s_nop 1
	v_mov_b32_e32 v17, v30
	v_pk_mul_f32 v[32:33], v[50:51], v[190:191] op_sel_hi:[1,0]
	v_pk_mul_f32 v[28:29], v[28:29], v[190:191] op_sel_hi:[1,0]
	v_pk_mul_f32 v[34:35], v[52:53], v[190:191] op_sel_hi:[1,0]
	v_pk_mul_f32 v[24:25], v[24:25], v[190:191] op_sel_hi:[1,0]
	v_pk_mul_f32 v[16:17], v[16:17], v[190:191] op_sel_hi:[1,0]
	v_mul_f32_e32 v21, 0xbfb8aa3b, v33
	v_mul_f32_e32 v30, 0xbfb8aa3b, v29
	v_exp_f32_e32 v21, v21
	v_exp_f32_e32 v30, v30
	v_mul_f32_e32 v36, 0xbfb8aa3b, v25
	v_mul_f32_e32 v37, 0xbfb8aa3b, v17
	v_add_f32_e32 v21, 1.0, v21
	v_add_f32_e32 v30, 1.0, v30
	v_rcp_f32_e32 v21, v21
	v_rcp_f32_e32 v30, v30
	v_exp_f32_e32 v36, v36
	v_exp_f32_e32 v37, v37
	v_mul_f32_e32 v21, v33, v21
	v_mul_f32_e32 v29, v29, v30
	v_mul_f32_e32 v21, v32, v21
	v_mul_f32_e32 v32, v28, v29
	v_mov_b32_e32 v28, v18
	v_mov_b32_e32 v29, v26
	v_add_f32_e32 v36, 1.0, v36
	v_add_f32_e32 v37, 1.0, v37
	v_pk_mul_f32 v[28:29], v[28:29], v[190:191] op_sel_hi:[1,0]
	v_rcp_f32_e32 v36, v36
	v_rcp_f32_e32 v30, v37
	v_mul_f32_e32 v18, 0xbfb8aa3b, v29
	v_exp_f32_e32 v18, v18
	v_mul_f32_e32 v25, v25, v36
	v_mul_f32_e32 v17, v17, v30
	v_mul_f32_e32 v24, v24, v25
	v_mul_f32_e32 v25, v16, v17
	v_add_f32_e32 v16, 1.0, v18
	v_mov_b32_e32 v30, v23
	v_rcp_f32_e32 v33, v16
	v_pk_mul_f32 v[16:17], v[30:31], v[190:191] op_sel_hi:[1,0]
	v_mov_b32_e32 v26, v19
	v_mul_f32_e32 v18, 0xbfb8aa3b, v17
	v_exp_f32_e32 v23, v18
	v_pk_mul_f32 v[18:19], v[26:27], v[190:191] op_sel_hi:[1,0]
	v_mul_f32_e32 v22, 0xbfb8aa3b, v35
	v_mul_f32_e32 v20, 0xbfb8aa3b, v19
	v_exp_f32_e32 v20, v20
	v_exp_f32_e32 v22, v22
	v_add_f32_e32 v23, 1.0, v23
	v_rcp_f32_e32 v23, v23
	v_add_f32_e32 v20, 1.0, v20
	v_rcp_f32_e32 v20, v20
	v_add_f32_e32 v22, 1.0, v22
	v_rcp_f32_e32 v22, v22
	v_mul_f32_e32 v17, v17, v23
	v_mul_f32_e32 v17, v16, v17
	v_mul_f32_e32 v16, v19, v20
	v_mul_f32_e32 v19, v18, v16
	v_cvt_pk_bf16_f32 v16, v21, v32
	v_add_u32_e32 v32, 0xb0, v144
	v_mul_f32_e32 v22, v35, v22
	v_mul_f32_e32 v26, v29, v33
	v_cvt_pk_bf16_f32 v17, v25, v17
	v_mad_i64_i32 v[20:21], s[4:5], v48, s63, v[116:117]
	v_ashrrev_i32_e32 v33, 31, v32
	v_mul_f32_e32 v22, v34, v22
	v_mul_f32_e32 v26, v28, v26
	v_cvt_pk_bf16_f32 v18, v22, v24
	v_cvt_pk_bf16_f32 v19, v26, v19
	global_store_dwordx4 v[20:21], v[16:19], off
	v_mov_b32_e32 v36, v0
	v_mov_b32_e32 v34, v4
	v_lshlrev_b64 v[16:17], 6, v[32:33]
	v_lshl_add_u64 v[28:29], s[18:19], 0, v[16:17]
	v_mov_b32_e32 v37, v8
	v_mov_b32_e32 v8, v1
	v_mov_b32_e32 v35, v12
	v_mov_b32_e32 v12, v5
	s_nop 0
	s_nop 0
	s_nop 1
	v_mov_b32_e32 v0, v6
	s_nop 1
	s_nop 1
	s_nop 1
	v_mov_b32_e32 v1, v14
	v_pk_mul_f32 v[16:17], v[34:35], v[192:193] op_sel_hi:[1,0]
	v_pk_mul_f32 v[18:19], v[36:37], v[192:193] op_sel_hi:[1,0]
	v_pk_mul_f32 v[12:13], v[12:13], v[192:193] op_sel_hi:[1,0]
	v_pk_mul_f32 v[8:9], v[8:9], v[192:193] op_sel_hi:[1,0]
	v_pk_mul_f32 v[0:1], v[0:1], v[192:193] op_sel_hi:[1,0]
	v_mul_f32_e32 v5, 0xbfb8aa3b, v17
	v_exp_f32_e32 v5, v5
	v_mul_f32_e32 v14, 0xbfb8aa3b, v13
	v_exp_f32_e32 v14, v14
	v_mul_f32_e32 v21, 0xbfb8aa3b, v1
	v_add_f32_e32 v5, 1.0, v5
	v_rcp_f32_e32 v5, v5
	v_add_f32_e32 v14, 1.0, v14
	v_rcp_f32_e32 v14, v14
	v_mul_f32_e32 v20, 0xbfb8aa3b, v9
	v_mul_f32_e32 v5, v17, v5
	v_mul_f32_e32 v5, v16, v5
	v_exp_f32_e32 v16, v21
	v_exp_f32_e32 v20, v20
	v_mul_f32_e32 v13, v13, v14
	v_mul_f32_e32 v17, v12, v13
	v_add_f32_e32 v12, 1.0, v16
	v_rcp_f32_e32 v14, v12
	v_mov_b32_e32 v12, v2
	v_mov_b32_e32 v13, v10
	v_add_f32_e32 v20, 1.0, v20
	v_pk_mul_f32 v[12:13], v[12:13], v[192:193] op_sel_hi:[1,0]
	v_rcp_f32_e32 v20, v20
	v_mul_f32_e32 v2, 0xbfb8aa3b, v13
	v_exp_f32_e32 v2, v2
	v_mul_f32_e32 v1, v1, v14
	v_mul_f32_e32 v9, v9, v20
	v_mul_f32_e32 v8, v8, v9
	v_mul_f32_e32 v9, v0, v1
	v_add_f32_e32 v0, 1.0, v2
	v_mov_b32_e32 v14, v7
	v_rcp_f32_e32 v16, v0
	v_pk_mul_f32 v[0:1], v[14:15], v[192:193] op_sel_hi:[1,0]
	v_mov_b32_e32 v10, v3
	v_mul_f32_e32 v2, 0xbfb8aa3b, v1
	v_exp_f32_e32 v7, v2
	v_pk_mul_f32 v[2:3], v[10:11], v[192:193] op_sel_hi:[1,0]
	v_mul_f32_e32 v6, 0xbfb8aa3b, v19
	v_mul_f32_e32 v4, 0xbfb8aa3b, v3
	v_exp_f32_e32 v4, v4
	v_exp_f32_e32 v6, v6
	v_add_f32_e32 v7, 1.0, v7
	v_rcp_f32_e32 v7, v7
	v_add_f32_e32 v4, 1.0, v4
	v_add_f32_e32 v6, 1.0, v6
	v_rcp_f32_e32 v4, v4
	v_rcp_f32_e32 v6, v6
	v_mul_f32_e32 v1, v1, v7
	v_mul_f32_e32 v1, v0, v1
	v_mul_f32_e32 v0, v3, v4
	v_mul_f32_e32 v6, v19, v6
	v_mul_f32_e32 v10, v13, v16
	v_mul_f32_e32 v3, v2, v0
	v_cvt_pk_bf16_f32 v0, v5, v17
	v_mad_i64_i32 v[4:5], s[4:5], v32, s63, v[116:117]
	s_andn2_b64 vcc, exec, s[2:3]
	s_mov_b64 s[2:3], -1
	v_mul_f32_e32 v6, v18, v6
	v_mul_f32_e32 v10, v12, v10
	v_cvt_pk_bf16_f32 v1, v9, v1
	v_cvt_pk_bf16_f32 v2, v6, v8
	v_cvt_pk_bf16_f32 v3, v10, v3
	global_store_dwordx4 v[4:5], v[0:3], off
	s_cbranch_vccnz .LBB0_1253
	s_andn2_b64 vcc, exec, s[10:11]
	s_cbranch_vccnz .LBB0_1252
	s_barrier
	s_branch .LBB0_1252

; #define LAS __attribute__((address_space(3)))
; __global__ void __launch_bounds__(512, 2) hybrid_fwd(Ctx c) {
;     extern __shared__ __attribute__((aligned(16))) unsigned char lds_raw[];
;     LAS unsigned char* lds = (LAS unsigned char*)lds_raw;
	.amdhsa_kernel _Z10hybrid_fwd3Ctx
		.amdhsa_group_segment_fixed_size 0
		.amdhsa_private_segment_fixed_size 0
		.amdhsa_kernarg_size 440
		.amdhsa_user_sgpr_count 2
		.amdhsa_user_sgpr_dispatch_ptr 0
		.amdhsa_user_sgpr_queue_ptr 0
		.amdhsa_user_sgpr_kernarg_segment_ptr 1
		.amdhsa_user_sgpr_dispatch_id 0
		.amdhsa_user_sgpr_kernarg_preload_length 0
		.amdhsa_user_sgpr_kernarg_preload_offset 0
		.amdhsa_user_sgpr_private_segment_size 0
		.amdhsa_uses_dynamic_stack 0
		.amdhsa_enable_private_segment 0
		.amdhsa_system_sgpr_workgroup_id_x 1
		.amdhsa_system_sgpr_workgroup_id_y 0
		.amdhsa_system_sgpr_workgroup_id_z 0
		.amdhsa_system_sgpr_workgroup_info 0
		.amdhsa_system_vgpr_workitem_id 2
		.amdhsa_next_free_vgpr 256
		.amdhsa_next_free_sgpr 102
		.amdhsa_accum_offset 256
		.amdhsa_reserve_vcc 1
		.amdhsa_float_round_mode_32 0
		.amdhsa_float_round_mode_16_64 0
		.amdhsa_float_denorm_mode_32 3
		.amdhsa_float_denorm_mode_16_64 3
		.amdhsa_dx10_clamp 1
		.amdhsa_ieee_mode 1
		.amdhsa_fp16_overflow 0
		.amdhsa_tg_split 0
		.amdhsa_exception_fp_ieee_invalid_op 0
		.amdhsa_exception_fp_denorm_src 0
		.amdhsa_exception_fp_ieee_div_zero 0
		.amdhsa_exception_fp_ieee_overflow 0
		.amdhsa_exception_fp_ieee_underflow 0
		.amdhsa_exception_fp_ieee_inexact 0
		.amdhsa_exception_int_div_zero 0
	.end_amdhsa_kernel

; __global__ void __launch_bounds__(512, 2) hybrid_fwd(Ctx c) {
amdhsa.kernels:
  - .agpr_count:     0
    .args:
      - .offset:         0
        .size:           184
        .value_kind:     by_value
      - .offset:         184
        .size:           4
        .value_kind:     hidden_block_count_x
      - .offset:         188
        .size:           4
        .value_kind:     hidden_block_count_y
      - .offset:         192
        .size:           4
        .value_kind:     hidden_block_count_z
      - .offset:         196
        .size:           2
        .value_kind:     hidden_group_size_x
      - .offset:         198
        .size:           2
        .value_kind:     hidden_group_size_y
      - .offset:         200
        .size:           2
        .value_kind:     hidden_group_size_z
      - .offset:         202
        .size:           2
        .value_kind:     hidden_remainder_x
      - .offset:         204
        .size:           2
        .value_kind:     hidden_remainder_y
      - .offset:         206
        .size:           2
        .value_kind:     hidden_remainder_z
      - .offset:         224
        .size:           8
        .value_kind:     hidden_global_offset_x
      - .offset:         232
        .size:           8
        .value_kind:     hidden_global_offset_y
      - .offset:         240
        .size:           8
        .value_kind:     hidden_global_offset_z
      - .offset:         248
        .size:           2
        .value_kind:     hidden_grid_dims
      - .offset:         272
        .size:           8
        .value_kind:     hidden_multigrid_sync_arg
      - .offset:         304
        .size:           4
        .value_kind:     hidden_dynamic_lds_size
    .group_segment_fixed_size: 0
    .kernarg_segment_align: 8
    .kernarg_segment_size: 440
    .language:       OpenCL C
    .language_version:
      - 2
      - 0
    .max_flat_workgroup_size: 512
    .name:           _Z10hybrid_fwd3Ctx
    .private_segment_fixed_size: 0
    .sgpr_count:     108
    .sgpr_spill_count: 33
    .symbol:         _Z10hybrid_fwd3Ctx.kd
    .uniform_work_group_size: 1
    .uses_dynamic_stack: false
    .vgpr_count:     256
    .vgpr_spill_count: 0
    .wavefront_size: 64
